# mLSTM q/k conv staging: neighbour rows read from adjacent lanes' staged rows in the 64-token-row segment (9 instead of 21 LDS-DMA loads per chunk)
# baseline (speedup 1.0000x reference)
; DI void mlstm_job(const PX& p, int l, int job, unsigned char* smem) {
;     ...
;       if (w == 0 && cc + 1 < 36) {
;         const int sg = (cc + 1) >= 4;
;         const int pos = (sg ? cc + 1 - 4 : cc + 1) * 64 + lane;
;         const int Ls = sg ? 2048 : 256;
;         const int t = dir ? Ls - 1 - pos : pos;
;         const int tok = (sg ? b * 2048 : NLAT + b * 256) + t;
;         pgi = Zgt[(size_t)tok * 16 + (dir ? 8 : 0) + h];
;         pgf = Zgt[(size_t)tok * 16 + (dir ? 12 : 4) + h];
;       }
;       const float dec = scA[par * 4];
;       const float mnew = scA[par * 4 + 1];
; #pragma unroll
;       for (int i = 0; i < 9; i++) {
;         const int u = tid + NTHR * i;
;         const int which = i / 3;
;         const int rem = u - which * 1536;
;         const int tau = rem & 63;
;         const int d8 = (rem >> 6) * 8;
;         const int pos = c * 64 + tau;
;         const int t = dir ? Lseg - 1 - pos : pos;
;         const int tok = tokbase + t;
;         if (which < 2) {
;           const bfu* zp = Zml + (size_t)tok * 3072 + which * 768 + h * 192 + d8;
;           const int tm = t & (RL - 1);
;           const uint4 mid = *(const uint4*)zp;
;           const uint4 lft = *(const uint4*)(zp - ((tm != 0) ? 3072 : 0));
;           const uint4 rgt = *(const uint4*)(zp + ((tm != RL - 1) ? 3072 : 0));
;           const float lvf = (tm != 0) ? 1.f : 0.f, rvf = (tm != RL - 1) ? 1.f : 0.f;
;           const unsigned ml_[4] = {lft.x, lft.y, lft.z, lft.w};
;           const unsigned mm_[4] = {mid.x, mid.y, mid.z, mid.w};
;           const unsigned mr_[4] = {rgt.x, rgt.y, rgt.z, rgt.w};
;           const float* cwx = cw + which * 192 + d8;
;           float v[8];
; #pragma unroll
;           for (int e = 0; e < 8; e++) {
;             const float a = (e & 1) ? hi16(ml_[e >> 1]) : lo16(ml_[e >> 1]);
;             const float bm = (e & 1) ? hi16(mm_[e >> 1]) : lo16(mm_[e >> 1]);
;             const float cr = (e & 1) ? hi16(mr_[e >> 1]) : lo16(mr_[e >> 1]);
;             float s = cwx[e] * (a * lvf) + cwx[384 + e] * bm + cwx[768 + e] * (cr * rvf) + cwx[1152 + e];
;             s = s / (1.f + __expf(-s));
;             v[e] = s;
;           }
;           if (which == 0) {
;             uint4 o;
;             o.x = pack2(v[0], v[1]); o.y = pack2(v[2], v[3]); o.z = pack2(v[4], v[5]); o.w = pack2(v[6], v[7]);
;             *(uint4*)(sq + tau * 200 + d8) = o;
.LBB0_449:
	s_and_b32 s0, s13, 1
	s_add_i32 s2, s10, 0xffffff00
	s_cmp_gt_u32 s13, 3
	s_movk_i32 s3, 0x800
	s_cselect_b32 s26, s2, s10
	s_cselect_b32 s3, s3, 0x100
	s_cselect_b32 s2, s11, s12
	s_cselect_b32 s1, 63, 0xff
	v_or_b32_e32 v0, s26, v175
	v_xad_u32 v2, v0, -1, s3
	v_cndmask_b32_e64 v0, v2, v0, s[4:5]
	v_add_u32_e32 v4, s2, v0
	v_mov_b64_e32 v[2:3], s[74:75]
	s_movk_i32 s2, 0x1800
	v_mad_i64_i32 v[124:125], s[26:27], v4, s2, v[2:3]
	v_and_b32_e32 v0, s1, v0
	v_cmp_eq_u32_e32 vcc, 0, v0
	v_mov_b32_e32 v2, 0xffffe800
	v_lshl_add_u64 v[14:15], v[168:169], 1, v[124:125]
	v_cndmask_b32_e64 v127, -1, 0, vcc
	v_cndmask_b32_e64 v126, v2, 0, vcc
	v_lshl_add_u64 v[154:155], v[14:15], 0, v[126:127]
	v_cmp_eq_u32_e64 s[2:3], s1, v0
	s_nop 1
	v_cndmask_b32_e64 v0, v214, 0, s[2:3]
	v_lshl_add_u64 v[156:157], v[14:15], 0, v[0:1]
	s_cmp_gt_u32 s13, 3
	s_cbranch_scc1 .Lnb_new
	v_add_u32_e32 v217, 0x2000, v208
	v_add_u32_e32 v218, 0x4000, v208
	s_branch .Lnb_set
.Lnb_new:
	v_cmp_ne_u32_e32 vcc, 0, v211
	v_add_u32_e32 v209, -16, v208
	s_nop 1
	v_cndmask_b32_e32 v217, v208, v209, vcc
	v_cmp_ne_u32_e32 vcc, 63, v211
	v_add_u32_e32 v209, 16, v208
	s_nop 1
	v_cndmask_b32_e32 v218, v208, v209, vcc
	v_cndmask_b32_e64 v209, v218, v217, s[4:5]
	v_cndmask_b32_e64 v218, v217, v218, s[4:5]
	v_mov_b32_e32 v217, v209
.Lnb_set:
	s_add_i32 m0, s82, 0x21100
	s_nop 0
	global_load_lds_dwordx4 v[14:15], off
	s_cmp_gt_u32 s13, 3
	s_cbranch_scc1 .Lnb_sk0
	s_add_i32 m0, s82, 0x23100
	s_nop 0
	global_load_lds_dwordx4 v[154:155], off
	s_add_i32 m0, s82, 0x25100
	s_nop 0
	global_load_lds_dwordx4 v[156:157], off
.Lnb_sk0:
.LBB0_452:
	s_or_b64 exec, exec, s[62:63]
	s_cmp_lg_u32 s13, 35
	s_cselect_b64 s[2:3], -1, 0
	s_and_b64 s[2:3], s[76:77], s[2:3]
	s_waitcnt lgkmcnt(0)
	s_barrier
	s_waitcnt vmcnt(0)
	s_and_saveexec_b64 s[62:63], s[2:3]
	s_cbranch_execz .LBB0_454
	s_cmp_gt_u32 s13, 2
	s_cselect_b32 s1, -3, 1
	s_movk_i32 s2, 0x7ff
	s_cselect_b32 s2, s2, 0xff
	s_cselect_b32 s3, s11, s12
	s_add_i32 s1, s1, s13
	v_lshl_or_b32 v0, s1, 6, v175
	v_sub_u32_e32 v2, s2, v0
	v_cndmask_b32_e64 v0, v2, v0, s[4:5]
	v_add_u32_e32 v2, s3, v0
	v_ashrrev_i32_e32 v3, 31, v2
	v_readlane_b32 s2, v254, 14
	v_lshlrev_b64 v[2:3], 6, v[2:3]
	v_readlane_b32 s3, v254, 15
	s_nop 1
	v_lshl_add_u64 v[2:3], s[2:3], 0, v[2:3]
	v_readlane_b32 s2, v253, 31
	v_readlane_b32 s3, v253, 32
	s_mov_b32 s61, s3
	s_mov_b32 s69, s3
	v_lshl_add_u64 v[4:5], v[2:3], 0, s[2:3]
	v_lshl_add_u64 v[4:5], v[4:5], 0, s[60:61]
	v_lshl_add_u64 v[2:3], v[2:3], 0, s[68:69]
	v_lshl_add_u64 v[2:3], v[2:3], 0, s[60:61]
	global_load_dword v177, v[4:5], off
	global_load_dword v180, v[2:3], off
.LBB0_454:
	s_or_b64 exec, exec, s[62:63]
	s_lshl_b32 s1, s0, 4
	s_or_b32 s1, s1, 0x1e000
	s_add_i32 s2, s10, 0xffffff00
	s_cmp_gt_u32 s13, 3
	s_movk_i32 s3, 0x800
	v_mov_b32_e32 v0, s1
	s_cselect_b32 s26, s2, s10
	s_cselect_b32 s69, s3, 0x100
	ds_read_b64 v[162:163], v0
	v_or_b32_e32 v0, s26, v175
	v_xad_u32 v2, v0, -1, s69
	s_cselect_b32 s61, s11, s12
	v_cndmask_b32_e64 v0, v2, v0, s[4:5]
	v_add_u32_e32 v4, s61, v0
	v_mov_b64_e32 v[2:3], s[74:75]
	s_movk_i32 s1, 0x1800
	v_mad_i64_i32 v[124:125], s[2:3], v4, s1, v[2:3]
	s_cselect_b32 s1, 63, 0xff
	v_and_b32_e32 v0, s1, v0
	v_cmp_eq_u32_e32 vcc, 0, v0
	v_mov_b32_e32 v2, 0xffffe800
	v_lshl_add_u64 v[14:15], v[168:169], 1, v[124:125]
	v_cndmask_b32_e64 v127, -1, 0, vcc
	v_cndmask_b32_e64 v126, v2, 0, vcc
	v_lshl_add_u64 v[120:121], v[14:15], 0, v[126:127]
	ds_read_b128 v[2:5], v208
	ds_read_b128 v[6:9], v217
	v_cmp_eq_u32_e64 s[62:63], s1, v0
	v_cndmask_b32_e64 v118, 1.0, 0, vcc
	s_lshl_b32 s27, s0, 8
	v_cndmask_b32_e64 v0, v214, 0, s[62:63]
	v_lshl_add_u64 v[122:123], v[14:15], 0, v[0:1]
	ds_read_b128 v[10:13], v218
	s_waitcnt lgkmcnt(0)
	s_add_i32 m0, s82, 0x21080
	s_nop 0
	global_load_lds_dwordx4 v[14:15], off offset:128
	s_cmp_gt_u32 s13, 3
	s_cbranch_scc1 .Lnb_sk1
	s_add_i32 m0, s82, 0x23080
	s_nop 0
	global_load_lds_dwordx4 v[154:155], off offset:128
	s_add_i32 m0, s82, 0x25080
	s_nop 0
	global_load_lds_dwordx4 v[156:157], off offset:128
.Lnb_sk1:
	ds_read_b128 v[128:131], v196
	ds_read_b128 v[112:115], v196 offset:16
	v_cndmask_b32_e64 v116, 1.0, 0, s[62:63]
	v_add_u32_e32 v117, s27, v178
	s_mov_b32 s2, 0x3d93cd3a
	s_nop 0
	v_lshlrev_b32_e32 v136, 16, v2
	s_nop 0
	v_lshlrev_b32_e32 v132, 16, v6
	v_and_b32_e32 v133, 0xffff0000, v6
	v_pk_mul_f32 v[138:139], v[118:119], v[132:133] op_sel_hi:[0,1]
	ds_read_b128 v[132:135], v196 offset:1536
	v_and_b32_e32 v137, 0xffff0000, v2
	s_nop 0
	v_lshlrev_b32_e32 v140, 16, v10
	v_and_b32_e32 v141, 0xffff0000, v10
	s_waitcnt lgkmcnt(0)
	v_pk_mul_f32 v[132:133], v[132:133], v[136:137]
	s_nop 0
	v_pk_fma_f32 v[128:129], v[138:139], v[128:129], v[132:133]
	ds_read_b128 v[136:139], v196 offset:3072
	v_pk_mul_f32 v[132:133], v[116:117], v[140:141] op_sel_hi:[0,1]
	ds_read_b128 v[140:143], v196 offset:4608
	s_waitcnt lgkmcnt(1)
	v_pk_fma_f32 v[128:129], v[132:133], v[136:137], v[128:129]
	s_waitcnt lgkmcnt(0)
; DI unsigned pack2(float a, float b) { f32x2_t v = {a, b}; bf16x2_t r = __builtin_convertvector(v, bf16x2_t); return __builtin_bit_cast(unsigned, r); }
; DI float lo16(unsigned u) { return __uint_as_float(u << 16); }
; DI float hi16(unsigned u) { return __uint_as_float(u & 0xffff0000u); }
; DI void mlstm_job(const PX& p, int l, int job, unsigned char* smem) {
;     ...
;         if (which < 2) {
;           const bfu* zp = Zml + (size_t)tok * 3072 + which * 768 + h * 192 + d8;
;           const int tm = t & (RL - 1);
;           const uint4 mid = *(const uint4*)zp;
;           const uint4 lft = *(const uint4*)(zp - ((tm != 0) ? 3072 : 0));
;           const uint4 rgt = *(const uint4*)(zp + ((tm != RL - 1) ? 3072 : 0));
;           const float lvf = (tm != 0) ? 1.f : 0.f, rvf = (tm != RL - 1) ? 1.f : 0.f;
;           const unsigned ml_[4] = {lft.x, lft.y, lft.z, lft.w};
;           const unsigned mm_[4] = {mid.x, mid.y, mid.z, mid.w};
;           const unsigned mr_[4] = {rgt.x, rgt.y, rgt.z, rgt.w};
;           const float* cwx = cw + which * 192 + d8;
;           float v[8];
; #pragma unroll
;           for (int e = 0; e < 8; e++) {
;             const float a = (e & 1) ? hi16(ml_[e >> 1]) : lo16(ml_[e >> 1]);
;             const float bm = (e & 1) ? hi16(mm_[e >> 1]) : lo16(mm_[e >> 1]);
;             const float cr = (e & 1) ? hi16(mr_[e >> 1]) : lo16(mr_[e >> 1]);
;             float s = cwx[e] * (a * lvf) + cwx[384 + e] * bm + cwx[768 + e] * (cr * rvf) + cwx[1152 + e];
;             s = s / (1.f + __expf(-s));
;             v[e] = s;
;           }
;           if (which == 0) {
;             uint4 o;
;             o.x = pack2(v[0], v[1]); o.y = pack2(v[2], v[3]); o.z = pack2(v[4], v[5]); o.w = pack2(v[6], v[7]);
;             *(uint4*)(sq + tau * 200 + d8) = o;
	v_pk_add_f32 v[128:129], v[140:141], v[128:129]
	s_nop 0
	v_mul_f32_e32 v2, 0xbfb8aa3b, v128
	v_exp_f32_e32 v132, v2
	v_mul_f32_e32 v2, 0xbfb8aa3b, v129
	v_exp_f32_e32 v133, v2
	s_nop 0
	v_pk_add_f32 v[132:133], v[132:133], 1.0 op_sel_hi:[1,0]
	s_nop 0
	v_rcp_f32_e32 v6, v133
	s_nop 0
	v_mul_f32_e32 v119, v129, v6
	v_rcp_f32_e32 v6, v132
	s_nop 0
	v_mul_f32_e32 v128, v128, v6
	v_lshlrev_b32_e32 v6, 16, v7
	v_lshlrev_b32_e32 v2, 16, v3
	v_and_b32_e32 v7, 0xffff0000, v7
	v_and_b32_e32 v3, 0xffff0000, v3
	v_lshlrev_b32_e32 v10, 16, v11
	v_and_b32_e32 v11, 0xffff0000, v11
	v_pk_mul_f32 v[6:7], v[118:119], v[6:7] op_sel_hi:[0,1]
	v_pk_mul_f32 v[2:3], v[134:135], v[2:3]
	ds_read_b128 v[132:135], v196 offset:1552
	v_pk_fma_f32 v[2:3], v[6:7], v[130:131], v[2:3]
	v_pk_mul_f32 v[6:7], v[116:117], v[10:11] op_sel_hi:[0,1]
	v_pk_fma_f32 v[2:3], v[6:7], v[138:139], v[2:3]
	ds_read_b128 v[136:139], v196 offset:3088
	v_pk_add_f32 v[2:3], v[142:143], v[2:3]
	ds_read_b128 v[140:143], v196 offset:4624
	v_mul_f32_e32 v6, 0xbfb8aa3b, v2
	v_mul_f32_e32 v7, 0xbfb8aa3b, v3
	v_exp_f32_e32 v6, v6
	v_exp_f32_e32 v7, v7
	s_nop 0
	v_pk_add_f32 v[6:7], v[6:7], 1.0 op_sel_hi:[1,0]
	s_nop 0
	v_rcp_f32_e32 v11, v7
	s_nop 0
	v_mul_f32_e32 v129, v3, v11
	v_rcp_f32_e32 v7, v6
	s_nop 0
	v_mul_f32_e32 v130, v2, v7
	v_lshlrev_b32_e32 v10, 16, v8
	v_lshlrev_b32_e32 v6, 16, v4
	v_and_b32_e32 v11, 0xffff0000, v8
	v_and_b32_e32 v7, 0xffff0000, v4
	v_lshlrev_b32_e32 v2, 16, v12
	v_and_b32_e32 v3, 0xffff0000, v12
	v_pk_mul_f32 v[10:11], v[118:119], v[10:11] op_sel_hi:[0,1]
	s_waitcnt lgkmcnt(2)
	v_pk_mul_f32 v[6:7], v[132:133], v[6:7]
	v_pk_mul_f32 v[2:3], v[116:117], v[2:3] op_sel_hi:[0,1]
	v_pk_fma_f32 v[6:7], v[10:11], v[112:113], v[6:7]
	s_waitcnt lgkmcnt(1)
	v_pk_fma_f32 v[2:3], v[2:3], v[136:137], v[6:7]
	s_waitcnt lgkmcnt(0)
	v_pk_add_f32 v[2:3], v[140:141], v[2:3]
	s_nop 0
	v_mul_f32_e32 v4, 0xbfb8aa3b, v2
	v_exp_f32_e32 v6, v4
	v_mul_f32_e32 v4, 0xbfb8aa3b, v3
	v_exp_f32_e32 v7, v4
	s_nop 0
	v_pk_add_f32 v[6:7], v[6:7], 1.0 op_sel_hi:[1,0]
	s_nop 0
	v_rcp_f32_e32 v8, v7
	s_nop 0
	v_mul_f32_e32 v8, v3, v8
	v_rcp_f32_e32 v4, v6
	s_nop 0
	v_mul_f32_e32 v10, v2, v4
	v_lshlrev_b32_e32 v2, 16, v9
	v_lshlrev_b32_e32 v4, 16, v5
	v_and_b32_e32 v3, 0xffff0000, v9
	v_and_b32_e32 v5, 0xffff0000, v5
	v_lshlrev_b32_e32 v6, 16, v13
	v_and_b32_e32 v7, 0xffff0000, v13
	v_pk_mul_f32 v[2:3], v[118:119], v[2:3] op_sel_hi:[0,1]
	v_pk_mul_f32 v[4:5], v[134:135], v[4:5]
	s_nop 0
	v_pk_fma_f32 v[2:3], v[2:3], v[114:115], v[4:5]
	v_pk_mul_f32 v[4:5], v[116:117], v[6:7] op_sel_hi:[0,1]
	v_pk_fma_f32 v[2:3], v[4:5], v[138:139], v[2:3]
	s_nop 0
	v_pk_add_f32 v[2:3], v[142:143], v[2:3]
	s_nop 0
	v_mul_f32_e32 v4, 0xbfb8aa3b, v2
	v_mul_f32_e32 v5, 0xbfb8aa3b, v3
	v_exp_f32_e32 v4, v4
	v_exp_f32_e32 v5, v5
	s_nop 0
	v_pk_add_f32 v[4:5], v[4:5], 1.0 op_sel_hi:[1,0]
	s_nop 0
	v_rcp_f32_e32 v7, v5
	s_nop 0
	v_mul_f32_e32 v5, v3, v7
	v_rcp_f32_e32 v6, v4
	s_nop 0
	v_mul_f32_e32 v6, v2, v6
	v_cvt_pk_bf16_f32 v2, v128, v119
	v_cvt_pk_bf16_f32 v3, v130, v129
	v_cvt_pk_bf16_f32 v4, v10, v8
	v_cvt_pk_bf16_f32 v5, v6, v5
	ds_write_b128 v197, v[2:5]
	v_lshl_add_u64 v[4:5], v[170:171], 1, v[124:125]
	v_lshl_add_u64 v[10:11], v[4:5], 0, v[126:127]
	s_waitcnt vmcnt(0)
	ds_read_b128 v[6:9], v208
	ds_read_b128 v[112:115], v217
	v_lshl_add_u64 v[12:13], v[4:5], 0, v[0:1]
	ds_read_b128 v[128:131], v218
	s_waitcnt lgkmcnt(0)
	s_add_i32 m0, s82, 0x21000
	s_nop 0
	global_load_lds_dwordx4 v[14:15], off offset:256
	s_cmp_gt_u32 s13, 3
	s_cbranch_scc1 .Lnb_sk2
	s_add_i32 m0, s82, 0x23000
	s_nop 0
	global_load_lds_dwordx4 v[154:155], off offset:256
	s_add_i32 m0, s82, 0x25000
	s_nop 0
	global_load_lds_dwordx4 v[156:157], off offset:256
.Lnb_sk2:
	ds_read_b128 v[132:135], v198
	ds_read_b128 v[136:139], v198 offset:16
	ds_read_b128 v[140:143], v198 offset:1536
	s_nop 0
	v_lshlrev_b32_e32 v144, 16, v6
	s_nop 0
	v_lshlrev_b32_e32 v2, 16, v112
	v_and_b32_e32 v3, 0xffff0000, v112
	v_and_b32_e32 v145, 0xffff0000, v6
	s_nop 0
	v_lshlrev_b32_e32 v148, 16, v128
	v_and_b32_e32 v149, 0xffff0000, v128
	v_pk_mul_f32 v[2:3], v[118:119], v[2:3] op_sel_hi:[0,1]
	s_waitcnt lgkmcnt(0)
	v_pk_mul_f32 v[140:141], v[140:141], v[144:145]
	ds_read_b128 v[144:147], v198 offset:3072
	v_pk_fma_f32 v[2:3], v[2:3], v[132:133], v[140:141]
	v_pk_mul_f32 v[132:133], v[116:117], v[148:149] op_sel_hi:[0,1]
	ds_read_b128 v[148:151], v198 offset:4608
	s_waitcnt lgkmcnt(1)
	v_pk_fma_f32 v[2:3], v[132:133], v[144:145], v[2:3]
	s_waitcnt lgkmcnt(0)
	v_pk_add_f32 v[2:3], v[148:149], v[2:3]
	s_nop 0
	v_mul_f32_e32 v6, 0xbfb8aa3b, v2
	v_exp_f32_e32 v132, v6
	v_mul_f32_e32 v6, 0xbfb8aa3b, v3
	v_exp_f32_e32 v133, v6
	s_nop 0
	v_pk_add_f32 v[132:133], v[132:133], 1.0 op_sel_hi:[1,0]
	s_nop 0
	v_rcp_f32_e32 v112, v133
	s_nop 0
	v_mul_f32_e32 v119, v3, v112
	v_rcp_f32_e32 v6, v132
	s_nop 0
	v_mul_f32_e32 v128, v2, v6
	v_lshlrev_b32_e32 v2, 16, v113
	v_lshlrev_b32_e32 v6, 16, v7
	v_and_b32_e32 v3, 0xffff0000, v113
	v_and_b32_e32 v7, 0xffff0000, v7
	v_lshlrev_b32_e32 v112, 16, v129
	v_and_b32_e32 v113, 0xffff0000, v129
	v_pk_mul_f32 v[2:3], v[118:119], v[2:3] op_sel_hi:[0,1]
	v_pk_mul_f32 v[6:7], v[142:143], v[6:7]
	ds_read_b128 v[140:143], v198 offset:3088
	v_pk_fma_f32 v[2:3], v[2:3], v[134:135], v[6:7]
	v_pk_mul_f32 v[6:7], v[116:117], v[112:113] op_sel_hi:[0,1]
	v_pk_fma_f32 v[2:3], v[6:7], v[146:147], v[2:3]
	ds_read_b128 v[144:147], v198 offset:4624
	v_pk_add_f32 v[2:3], v[150:151], v[2:3]
	s_nop 0
	v_mul_f32_e32 v6, 0xbfb8aa3b, v2
	v_mul_f32_e32 v7, 0xbfb8aa3b, v3
	v_exp_f32_e32 v6, v6
	v_exp_f32_e32 v7, v7
	s_nop 0
	v_pk_add_f32 v[6:7], v[6:7], 1.0 op_sel_hi:[1,0]
	s_nop 0
	v_rcp_f32_e32 v113, v7
	s_nop 0
	v_mul_f32_e32 v129, v3, v113
	v_rcp_f32_e32 v7, v6
	s_nop 0
	ds_read_b128 v[132:135], v198 offset:1552
	v_mul_f32_e32 v148, v2, v7
	v_lshlrev_b32_e32 v2, 16, v114
	v_lshlrev_b32_e32 v6, 16, v8
	v_and_b32_e32 v3, 0xffff0000, v114
	v_and_b32_e32 v7, 0xffff0000, v8
	v_lshlrev_b32_e32 v112, 16, v130
	v_and_b32_e32 v113, 0xffff0000, v130
	v_pk_mul_f32 v[2:3], v[118:119], v[2:3] op_sel_hi:[0,1]
	s_waitcnt lgkmcnt(0)
; DI unsigned pack2(float a, float b) { f32x2_t v = {a, b}; bf16x2_t r = __builtin_convertvector(v, bf16x2_t); return __builtin_bit_cast(unsigned, r); }
; DI float lo16(unsigned u) { return __uint_as_float(u << 16); }
; DI float hi16(unsigned u) { return __uint_as_float(u & 0xffff0000u); }
; DI void mlstm_job(const PX& p, int l, int job, unsigned char* smem) {
;     ...
;         if (which < 2) {
;           const bfu* zp = Zml + (size_t)tok * 3072 + which * 768 + h * 192 + d8;
;           const int tm = t & (RL - 1);
;           const uint4 mid = *(const uint4*)zp;
;           const uint4 lft = *(const uint4*)(zp - ((tm != 0) ? 3072 : 0));
;           const uint4 rgt = *(const uint4*)(zp + ((tm != RL - 1) ? 3072 : 0));
;           const float lvf = (tm != 0) ? 1.f : 0.f, rvf = (tm != RL - 1) ? 1.f : 0.f;
;           const unsigned ml_[4] = {lft.x, lft.y, lft.z, lft.w};
;           const unsigned mm_[4] = {mid.x, mid.y, mid.z, mid.w};
;           const unsigned mr_[4] = {rgt.x, rgt.y, rgt.z, rgt.w};
;           const float* cwx = cw + which * 192 + d8;
;           float v[8];
; #pragma unroll
;           for (int e = 0; e < 8; e++) {
;             const float a = (e & 1) ? hi16(ml_[e >> 1]) : lo16(ml_[e >> 1]);
;             const float bm = (e & 1) ? hi16(mm_[e >> 1]) : lo16(mm_[e >> 1]);
;             const float cr = (e & 1) ? hi16(mr_[e >> 1]) : lo16(mr_[e >> 1]);
;             float s = cwx[e] * (a * lvf) + cwx[384 + e] * bm + cwx[768 + e] * (cr * rvf) + cwx[1152 + e];
;             s = s / (1.f + __expf(-s));
;             v[e] = s;
;           }
;           if (which == 0) {
;             uint4 o;
;             o.x = pack2(v[0], v[1]); o.y = pack2(v[2], v[3]); o.z = pack2(v[4], v[5]); o.w = pack2(v[6], v[7]);
;             *(uint4*)(sq + tau * 200 + d8) = o;
	v_pk_mul_f32 v[6:7], v[132:133], v[6:7]
	s_nop 0
	v_pk_fma_f32 v[2:3], v[2:3], v[136:137], v[6:7]
	v_pk_mul_f32 v[6:7], v[116:117], v[112:113] op_sel_hi:[0,1]
	v_pk_fma_f32 v[2:3], v[6:7], v[140:141], v[2:3]
	s_nop 0
	v_pk_add_f32 v[2:3], v[144:145], v[2:3]
	s_nop 0
	v_mul_f32_e32 v6, 0xbfb8aa3b, v2
	v_mul_f32_e32 v7, 0xbfb8aa3b, v3
	v_exp_f32_e32 v6, v6
	v_exp_f32_e32 v7, v7
	s_nop 0
	v_pk_add_f32 v[6:7], v[6:7], 1.0 op_sel_hi:[1,0]
	s_nop 0
	v_rcp_f32_e32 v112, v7
	s_nop 0
	v_mul_f32_e32 v112, v3, v112
	v_rcp_f32_e32 v7, v6
	s_nop 0
	v_mul_f32_e32 v113, v2, v7
	v_lshlrev_b32_e32 v2, 16, v115
	v_lshlrev_b32_e32 v6, 16, v9
	v_and_b32_e32 v3, 0xffff0000, v115
	v_and_b32_e32 v7, 0xffff0000, v9
	v_lshlrev_b32_e32 v8, 16, v131
	v_and_b32_e32 v9, 0xffff0000, v131
	v_pk_mul_f32 v[2:3], v[118:119], v[2:3] op_sel_hi:[0,1]
	v_pk_mul_f32 v[6:7], v[134:135], v[6:7]
	s_nop 0
	v_pk_fma_f32 v[2:3], v[2:3], v[138:139], v[6:7]
	v_pk_mul_f32 v[6:7], v[116:117], v[8:9] op_sel_hi:[0,1]
	v_pk_fma_f32 v[2:3], v[6:7], v[142:143], v[2:3]
	s_nop 0
	v_pk_add_f32 v[2:3], v[146:147], v[2:3]
	s_nop 0
	v_mul_f32_e32 v6, 0xbfb8aa3b, v2
	v_mul_f32_e32 v7, 0xbfb8aa3b, v3
	v_exp_f32_e32 v6, v6
	v_exp_f32_e32 v7, v7
	s_nop 0
	v_pk_add_f32 v[6:7], v[6:7], 1.0 op_sel_hi:[1,0]
	s_nop 0
	v_rcp_f32_e32 v9, v7
	s_nop 0
	v_mul_f32_e32 v3, v3, v9
	v_rcp_f32_e32 v8, v6
	s_nop 0
	v_mul_f32_e32 v2, v2, v8
	v_cvt_pk_bf16_f32 v6, v128, v119
	v_cvt_pk_bf16_f32 v7, v148, v129
	v_cvt_pk_bf16_f32 v8, v113, v112
	v_cvt_pk_bf16_f32 v9, v2, v3
	v_lshl_add_u64 v[2:3], v[172:173], 1, v[124:125]
	ds_write_b128 v199, v[6:9]
	v_lshl_add_u64 v[6:7], v[2:3], 0, v[126:127]
	s_waitcnt vmcnt(0)
	ds_read_b128 v[112:115], v208
	ds_read_b128 v[124:127], v217
	v_lshl_add_u64 v[8:9], v[2:3], 0, v[0:1]
	ds_read_b128 v[128:131], v218
	s_waitcnt lgkmcnt(0)
	s_add_i32 m0, s82, 0x20b00
	s_nop 0
	global_load_lds_dwordx4 v[14:15], off offset:1536
	s_cmp_gt_u32 s13, 3
	s_cbranch_scc1 .Lnb_sk3
	s_add_i32 m0, s82, 0x22b00
	s_nop 0
	global_load_lds_dwordx4 v[154:155], off offset:1536
	s_add_i32 m0, s82, 0x24b00
	s_nop 0
	global_load_lds_dwordx4 v[156:157], off offset:1536
.Lnb_sk3:
	ds_read_b128 v[132:135], v200
	ds_read_b128 v[136:139], v200 offset:16
	s_nop 0
	v_lshlrev_b32_e32 v144, 16, v112
	s_nop 0
	v_lshlrev_b32_e32 v140, 16, v124
	v_and_b32_e32 v141, 0xffff0000, v124
	v_pk_mul_f32 v[146:147], v[118:119], v[140:141] op_sel_hi:[0,1]
	ds_read_b128 v[140:143], v200 offset:1536
	v_and_b32_e32 v145, 0xffff0000, v112
	s_nop 0
	v_lshlrev_b32_e32 v148, 16, v128
	v_and_b32_e32 v149, 0xffff0000, v128
	s_waitcnt lgkmcnt(0)
	v_pk_mul_f32 v[140:141], v[140:141], v[144:145]
	s_nop 0
	v_pk_fma_f32 v[132:133], v[146:147], v[132:133], v[140:141]
	ds_read_b128 v[144:147], v200 offset:3072
	v_pk_mul_f32 v[140:141], v[116:117], v[148:149] op_sel_hi:[0,1]
	ds_read_b128 v[148:151], v200 offset:4608
	s_waitcnt lgkmcnt(1)
	v_pk_fma_f32 v[132:133], v[140:141], v[144:145], v[132:133]
	s_waitcnt lgkmcnt(0)
	v_pk_add_f32 v[132:133], v[148:149], v[132:133]
	s_nop 0
	v_mul_f32_e32 v0, 0xbfb8aa3b, v132
	v_exp_f32_e32 v140, v0
	v_mul_f32_e32 v0, 0xbfb8aa3b, v133
	v_exp_f32_e32 v141, v0
	s_nop 0
	v_pk_add_f32 v[140:141], v[140:141], 1.0 op_sel_hi:[1,0]
	s_nop 0
	v_rcp_f32_e32 v112, v141
	s_nop 0
	v_mul_f32_e32 v0, v133, v112
	v_rcp_f32_e32 v119, v140
	s_nop 0
	v_mul_f32_e32 v119, v132, v119
	v_lshlrev_b32_e32 v124, 16, v125
	v_lshlrev_b32_e32 v112, 16, v113
	v_and_b32_e32 v125, 0xffff0000, v125
	v_and_b32_e32 v113, 0xffff0000, v113
	v_lshlrev_b32_e32 v128, 16, v129
	v_and_b32_e32 v129, 0xffff0000, v129
	v_pk_mul_f32 v[124:125], v[118:119], v[124:125] op_sel_hi:[0,1]
	v_pk_mul_f32 v[112:113], v[142:143], v[112:113]
	ds_read_b128 v[140:143], v200 offset:3088
	v_pk_fma_f32 v[112:113], v[124:125], v[134:135], v[112:113]
	v_pk_mul_f32 v[124:125], v[116:117], v[128:129] op_sel_hi:[0,1]
	v_pk_fma_f32 v[112:113], v[124:125], v[146:147], v[112:113]
	ds_read_b128 v[144:147], v200 offset:4624
	v_pk_add_f32 v[112:113], v[150:151], v[112:113]
	s_nop 0
	v_mul_f32_e32 v124, 0xbfb8aa3b, v112
	v_mul_f32_e32 v125, 0xbfb8aa3b, v113
	v_exp_f32_e32 v124, v124
	v_exp_f32_e32 v125, v125
	s_nop 0
	v_pk_add_f32 v[124:125], v[124:125], 1.0 op_sel_hi:[1,0]
	s_nop 0
	v_rcp_f32_e32 v129, v125
	s_nop 0
	v_mul_f32_e32 v148, v113, v129
	v_rcp_f32_e32 v125, v124
	s_nop 0
	ds_read_b128 v[132:135], v200 offset:1552
	v_mul_f32_e32 v149, v112, v125
	v_lshlrev_b32_e32 v112, 16, v126
	v_lshlrev_b32_e32 v124, 16, v114
	v_and_b32_e32 v113, 0xffff0000, v126
	v_and_b32_e32 v125, 0xffff0000, v114
	v_lshlrev_b32_e32 v128, 16, v130
	v_and_b32_e32 v129, 0xffff0000, v130
	v_pk_mul_f32 v[112:113], v[118:119], v[112:113] op_sel_hi:[0,1]
	s_waitcnt lgkmcnt(0)
	v_pk_mul_f32 v[124:125], v[132:133], v[124:125]
	s_nop 0
	v_pk_fma_f32 v[112:113], v[112:113], v[136:137], v[124:125]
	v_pk_mul_f32 v[124:125], v[116:117], v[128:129] op_sel_hi:[0,1]
	v_pk_fma_f32 v[112:113], v[124:125], v[140:141], v[112:113]
	s_nop 0
	v_pk_add_f32 v[112:113], v[144:145], v[112:113]
	s_nop 0
	v_mul_f32_e32 v114, 0xbfb8aa3b, v112
	v_exp_f32_e32 v124, v114
	v_mul_f32_e32 v114, 0xbfb8aa3b, v113
	v_exp_f32_e32 v125, v114
	s_nop 0
	v_pk_add_f32 v[124:125], v[124:125], 1.0 op_sel_hi:[1,0]
	s_nop 0
	v_rcp_f32_e32 v126, v125
	s_nop 0
	v_mul_f32_e32 v126, v113, v126
	v_rcp_f32_e32 v114, v124
	s_nop 0
	v_mul_f32_e32 v128, v112, v114
	v_lshlrev_b32_e32 v112, 16, v127
	v_lshlrev_b32_e32 v114, 16, v115
	v_and_b32_e32 v113, 0xffff0000, v127
	v_and_b32_e32 v115, 0xffff0000, v115
	v_lshlrev_b32_e32 v124, 16, v131
	v_and_b32_e32 v125, 0xffff0000, v131
	v_pk_mul_f32 v[112:113], v[118:119], v[112:113] op_sel_hi:[0,1]
	v_pk_mul_f32 v[114:115], v[134:135], v[114:115]
	s_nop 0
	v_pk_fma_f32 v[112:113], v[112:113], v[138:139], v[114:115]
	v_pk_mul_f32 v[114:115], v[116:117], v[124:125] op_sel_hi:[0,1]
	v_pk_fma_f32 v[112:113], v[114:115], v[142:143], v[112:113]
	s_nop 0
	v_pk_add_f32 v[112:113], v[146:147], v[112:113]
	s_nop 0
	v_mul_f32_e32 v114, 0xbfb8aa3b, v112
	v_mul_f32_e32 v115, 0xbfb8aa3b, v113
	v_exp_f32_e32 v114, v114
	v_exp_f32_e32 v115, v115
	s_nop 0
	v_pk_add_f32 v[114:115], v[114:115], 1.0 op_sel_hi:[1,0]
	s_nop 0
	v_rcp_f32_e32 v125, v115
	s_nop 0
	v_mul_f32_e32 v115, v113, v125
	v_rcp_f32_e32 v124, v114
	s_nop 0
	v_mul_f32_e32 v124, v112, v124
	v_cvt_pk_bf16_f32 v112, v119, v0
	v_cvt_pk_bf16_f32 v113, v149, v148
	v_cvt_pk_bf16_f32 v114, v128, v126
	v_cvt_pk_bf16_f32 v115, v124, v115
	ds_write_b128 v201, v[112:115]
	s_waitcnt vmcnt(0)
	ds_read_b128 v[112:115], v208
	ds_read_b128 v[124:127], v217
	s_nop 0
	ds_read_b128 v[120:123], v218
	s_waitcnt lgkmcnt(0)
	s_add_i32 m0, s82, 0x20a80
	s_nop 0
	global_load_lds_dwordx4 v[14:15], off offset:1664
	s_cmp_gt_u32 s13, 3
	s_cbranch_scc1 .Lnb_sk4
	s_add_i32 m0, s82, 0x22a80
	s_nop 0
	global_load_lds_dwordx4 v[154:155], off offset:1664
	s_add_i32 m0, s82, 0x24a80
	s_nop 0
	global_load_lds_dwordx4 v[156:157], off offset:1664
; DI unsigned pack2(float a, float b) { f32x2_t v = {a, b}; bf16x2_t r = __builtin_convertvector(v, bf16x2_t); return __builtin_bit_cast(unsigned, r); }
; DI float lo16(unsigned u) { return __uint_as_float(u << 16); }
; DI float hi16(unsigned u) { return __uint_as_float(u & 0xffff0000u); }
; DI void mlstm_job(const PX& p, int l, int job, unsigned char* smem) {
;     ...
;         if (which < 2) {
;           const bfu* zp = Zml + (size_t)tok * 3072 + which * 768 + h * 192 + d8;
;           const int tm = t & (RL - 1);
;           const uint4 mid = *(const uint4*)zp;
;           const uint4 lft = *(const uint4*)(zp - ((tm != 0) ? 3072 : 0));
;           const uint4 rgt = *(const uint4*)(zp + ((tm != RL - 1) ? 3072 : 0));
;           const float lvf = (tm != 0) ? 1.f : 0.f, rvf = (tm != RL - 1) ? 1.f : 0.f;
;           const unsigned ml_[4] = {lft.x, lft.y, lft.z, lft.w};
;           const unsigned mm_[4] = {mid.x, mid.y, mid.z, mid.w};
;           const unsigned mr_[4] = {rgt.x, rgt.y, rgt.z, rgt.w};
;           const float* cwx = cw + which * 192 + d8;
;           float v[8];
; #pragma unroll
;           for (int e = 0; e < 8; e++) {
;             const float a = (e & 1) ? hi16(ml_[e >> 1]) : lo16(ml_[e >> 1]);
;             const float bm = (e & 1) ? hi16(mm_[e >> 1]) : lo16(mm_[e >> 1]);
;             const float cr = (e & 1) ? hi16(mr_[e >> 1]) : lo16(mr_[e >> 1]);
;             float s = cwx[e] * (a * lvf) + cwx[384 + e] * bm + cwx[768 + e] * (cr * rvf) + cwx[1152 + e];
;             s = s / (1.f + __expf(-s));
;             v[e] = s;
;           }
;           if (which == 0) {
;             uint4 o;
;             o.x = pack2(v[0], v[1]); o.y = pack2(v[2], v[3]); o.z = pack2(v[4], v[5]); o.w = pack2(v[6], v[7]);
;             *(uint4*)(sq + tau * 200 + d8) = o;
;           } else {
;             const float wk = wkA[par * 64 + tau];
; #pragma unroll
;             for (int e = 0; e < 8; e++) v[e] *= 0.07216878364870323f;
;             uint4 o;
;             o.x = pack2(v[0], v[1]); o.y = pack2(v[2], v[3]); o.z = pack2(v[4], v[5]); o.w = pack2(v[6], v[7]);
;             *(uint4*)(sk + tau * 200 + d8) = o;
; #pragma unroll
;             for (int e = 0; e < 8; e++) swk[(d8 + e) * 72 + tau] = f2bf(wk * v[e]);
;           }
.Lnb_sk4:
	s_nop 0
	v_lshlrev_b32_e32 v130, 16, v112
	s_nop 0
	v_lshlrev_b32_e32 v128, 16, v124
	s_nop 0
	v_lshlrev_b32_e32 v132, 16, v120
	v_and_b32_e32 v129, 0xffff0000, v124
	v_and_b32_e32 v131, 0xffff0000, v112
	v_and_b32_e32 v133, 0xffff0000, v120
	v_lshlrev_b32_e32 v136, 16, v125
	v_lshlrev_b32_e32 v138, 16, v113
	v_lshlrev_b32_e32 v140, 16, v121
	v_and_b32_e32 v137, 0xffff0000, v125
	v_and_b32_e32 v139, 0xffff0000, v113
	v_and_b32_e32 v141, 0xffff0000, v121
	v_lshlrev_b32_e32 v142, 16, v126
	v_lshlrev_b32_e32 v144, 16, v114
	v_lshlrev_b32_e32 v146, 16, v122
	v_and_b32_e32 v143, 0xffff0000, v126
	v_and_b32_e32 v145, 0xffff0000, v114
	v_and_b32_e32 v147, 0xffff0000, v122
	v_lshlrev_b32_e32 v148, 16, v127
	v_lshlrev_b32_e32 v150, 16, v115
	v_lshlrev_b32_e32 v152, 16, v123
	v_and_b32_e32 v149, 0xffff0000, v127
	v_and_b32_e32 v151, 0xffff0000, v115
	v_and_b32_e32 v153, 0xffff0000, v123
	ds_read_b32 v0, v117
	ds_read_b128 v[112:115], v202
	ds_read_b128 v[120:123], v202 offset:16
	ds_read_b128 v[124:127], v202 offset:1536
	v_pk_mul_f32 v[128:129], v[118:119], v[128:129] op_sel_hi:[0,1]
	s_waitcnt lgkmcnt(0)
	v_pk_mul_f32 v[124:125], v[124:125], v[130:131]
	s_nop 0
	v_pk_fma_f32 v[112:113], v[128:129], v[112:113], v[124:125]
	ds_read_b128 v[128:131], v202 offset:3072
	v_pk_mul_f32 v[124:125], v[116:117], v[132:133] op_sel_hi:[0,1]
	ds_read_b128 v[132:135], v202 offset:4608
	s_waitcnt lgkmcnt(1)
	v_pk_fma_f32 v[112:113], v[124:125], v[128:129], v[112:113]
	s_waitcnt lgkmcnt(0)
	v_pk_add_f32 v[112:113], v[132:133], v[112:113]
	s_nop 0
	v_mul_f32_e32 v119, 0xbfb8aa3b, v112
	v_exp_f32_e32 v124, v119
	v_mul_f32_e32 v119, 0xbfb8aa3b, v113
	v_exp_f32_e32 v125, v119
	s_nop 0
	v_pk_add_f32 v[124:125], v[124:125], 1.0 op_sel_hi:[1,0]
	s_nop 0
	v_rcp_f32_e32 v128, v125
	s_nop 0
	v_mul_f32_e32 v113, v113, v128
	v_rcp_f32_e32 v125, v124
	s_nop 0
	v_mul_f32_e32 v112, v112, v125
	v_pk_mul_f32 v[132:133], v[112:113], s[2:3] op_sel_hi:[1,0]
	v_pk_mul_f32 v[112:113], v[118:119], v[136:137] op_sel_hi:[0,1]
	v_pk_mul_f32 v[124:125], v[126:127], v[138:139]
	s_nop 0
	v_pk_fma_f32 v[112:113], v[112:113], v[114:115], v[124:125]
	v_pk_mul_f32 v[114:115], v[116:117], v[140:141] op_sel_hi:[0,1]
	v_pk_fma_f32 v[112:113], v[114:115], v[130:131], v[112:113]
	ds_read_b128 v[128:131], v202 offset:4624
	v_pk_add_f32 v[112:113], v[134:135], v[112:113]
	s_nop 0
	v_mul_f32_e32 v114, 0xbfb8aa3b, v112
	v_mul_f32_e32 v115, 0xbfb8aa3b, v113
	v_exp_f32_e32 v114, v114
	v_exp_f32_e32 v115, v115
	s_nop 0
	v_pk_add_f32 v[114:115], v[114:115], 1.0 op_sel_hi:[1,0]
	s_nop 0
	v_rcp_f32_e32 v124, v115
	s_nop 0
	v_mul_f32_e32 v113, v113, v124
	v_rcp_f32_e32 v119, v114
	s_nop 0
	v_mul_f32_e32 v112, v112, v119
	v_pk_mul_f32 v[134:135], v[112:113], s[2:3] op_sel_hi:[1,0]
	ds_read_b128 v[112:115], v202 offset:1552
	v_pk_mul_f32 v[124:125], v[118:119], v[142:143] op_sel_hi:[0,1]
	s_waitcnt lgkmcnt(0)
	v_pk_mul_f32 v[112:113], v[112:113], v[144:145]
	s_nop 0
	v_pk_fma_f32 v[112:113], v[124:125], v[120:121], v[112:113]
	ds_read_b128 v[124:127], v202 offset:3088
	v_pk_mul_f32 v[120:121], v[116:117], v[146:147] op_sel_hi:[0,1]
	v_pk_mul_f32 v[114:115], v[114:115], v[150:151]
	s_waitcnt lgkmcnt(0)
	v_pk_fma_f32 v[112:113], v[120:121], v[124:125], v[112:113]
	s_nop 0
	v_pk_add_f32 v[112:113], v[128:129], v[112:113]
	s_nop 0
	v_mul_f32_e32 v119, 0xbfb8aa3b, v112
	v_exp_f32_e32 v120, v119
	v_mul_f32_e32 v119, 0xbfb8aa3b, v113
	v_exp_f32_e32 v121, v119
	s_nop 0
	v_pk_add_f32 v[120:121], v[120:121], 1.0 op_sel_hi:[1,0]
	s_nop 0
	v_rcp_f32_e32 v124, v121
	s_nop 0
	v_mul_f32_e32 v113, v113, v124
	v_rcp_f32_e32 v121, v120
	s_nop 0
	v_mul_f32_e32 v112, v112, v121
	v_pk_mul_f32 v[120:121], v[112:113], s[2:3] op_sel_hi:[1,0]
	v_pk_mul_f32 v[112:113], v[118:119], v[148:149] op_sel_hi:[0,1]
	v_pk_fma_f32 v[112:113], v[112:113], v[122:123], v[114:115]
	v_pk_mul_f32 v[114:115], v[116:117], v[152:153] op_sel_hi:[0,1]
	v_pk_fma_f32 v[112:113], v[114:115], v[126:127], v[112:113]
	s_nop 0
	v_pk_add_f32 v[112:113], v[130:131], v[112:113]
	s_nop 0
	v_mul_f32_e32 v114, 0xbfb8aa3b, v112
	v_mul_f32_e32 v115, 0xbfb8aa3b, v113
	v_exp_f32_e32 v114, v114
	v_exp_f32_e32 v115, v115
	s_nop 0
	v_pk_add_f32 v[114:115], v[114:115], 1.0 op_sel_hi:[1,0]
	s_nop 0
	v_rcp_f32_e32 v122, v115
	s_nop 0
	v_mul_f32_e32 v113, v113, v122
	v_rcp_f32_e32 v119, v114
	s_nop 0
	v_mul_f32_e32 v112, v112, v119
	v_pk_mul_f32 v[122:123], v[112:113], s[2:3] op_sel_hi:[1,0]
	v_cvt_pk_bf16_f32 v112, v132, v133
	v_cvt_pk_bf16_f32 v113, v134, v135
	v_cvt_pk_bf16_f32 v114, v120, v121
	v_cvt_pk_bf16_f32 v115, v122, v123
	ds_write_b128 v203, v[112:115] offset:25600
	v_mul_f32_e32 v112, v132, v0
	v_cvt_pk_bf16_f32 v112, v112, s0
	v_add_u32_e32 v113, v181, v219
	ds_write_b16 v113, v112 offset:51200
	v_mul_f32_e32 v112, v133, v0
	v_cvt_pk_bf16_f32 v112, v112, s0
	ds_write_b16 v113, v112 offset:51344
	v_mul_f32_e32 v112, v134, v0
	v_cvt_pk_bf16_f32 v112, v112, s0
	ds_write_b16 v113, v112 offset:51488
	v_mul_f32_e32 v112, v135, v0
	v_cvt_pk_bf16_f32 v112, v112, s0
	ds_write_b16 v113, v112 offset:51632
	v_mul_f32_e32 v112, v120, v0
	v_cvt_pk_bf16_f32 v112, v112, s0
	ds_write_b16 v113, v112 offset:51776
	v_mul_f32_e32 v112, v121, v0
	v_cvt_pk_bf16_f32 v112, v112, s0
	ds_write_b16 v113, v112 offset:51920
	v_mul_f32_e32 v112, v0, v122
	v_cvt_pk_bf16_f32 v112, v112, s0
	v_mul_f32_e32 v0, v0, v123
	ds_write_b16 v113, v112 offset:52064
	v_cvt_pk_bf16_f32 v0, v0, s0
	v_add_u32_e32 v112, v181, v220
	ds_write_b16 v112, v0 offset:51200
	s_waitcnt vmcnt(0)
	ds_read_b128 v[112:115], v208
	ds_read_b128 v[120:123], v217
	s_nop 0
	ds_read_b128 v[10:13], v218
	s_waitcnt lgkmcnt(0)
	s_add_i32 m0, s82, 0x20a00
	s_nop 0
	global_load_lds_dwordx4 v[14:15], off offset:1792
	s_cmp_gt_u32 s13, 3
	s_cbranch_scc1 .Lnb_sk5
	s_add_i32 m0, s82, 0x22a00
	s_nop 0
	global_load_lds_dwordx4 v[154:155], off offset:1792
	s_add_i32 m0, s82, 0x24a00
	s_nop 0
	global_load_lds_dwordx4 v[156:157], off offset:1792
; DI unsigned pack2(float a, float b) { f32x2_t v = {a, b}; bf16x2_t r = __builtin_convertvector(v, bf16x2_t); return __builtin_bit_cast(unsigned, r); }
; DI void mlstm_job(const PX& p, int l, int job, unsigned char* smem) {
;     ...
;           } else {
;             const float wk = wkA[par * 64 + tau];
; #pragma unroll
;             for (int e = 0; e < 8; e++) v[e] *= 0.07216878364870323f;
;             uint4 o;
;             o.x = pack2(v[0], v[1]); o.y = pack2(v[2], v[3]); o.z = pack2(v[4], v[5]); o.w = pack2(v[6], v[7]);
;             *(uint4*)(sk + tau * 200 + d8) = o;
; #pragma unroll
;             for (int e = 0; e < 8; e++) swk[(d8 + e) * 72 + tau] = f2bf(wk * v[e]);
;           }
.Lnb_sk5:
	s_nop 0
	v_lshlrev_b32_e32 v126, 16, v112
	s_nop 0
	v_lshlrev_b32_e32 v124, 16, v120
	s_nop 0
	v_lshlrev_b32_e32 v128, 16, v10
	v_and_b32_e32 v125, 0xffff0000, v120
	v_and_b32_e32 v127, 0xffff0000, v112
	v_and_b32_e32 v129, 0xffff0000, v10
	v_lshlrev_b32_e32 v132, 16, v121
	v_lshlrev_b32_e32 v134, 16, v113
	v_lshlrev_b32_e32 v136, 16, v11
	v_and_b32_e32 v133, 0xffff0000, v121
	v_and_b32_e32 v135, 0xffff0000, v113
	v_and_b32_e32 v137, 0xffff0000, v11
	v_lshlrev_b32_e32 v138, 16, v122
	v_lshlrev_b32_e32 v140, 16, v114
	v_lshlrev_b32_e32 v142, 16, v12
	v_and_b32_e32 v139, 0xffff0000, v122
	v_and_b32_e32 v141, 0xffff0000, v114
	v_and_b32_e32 v143, 0xffff0000, v12
	v_lshlrev_b32_e32 v144, 16, v123
	v_lshlrev_b32_e32 v146, 16, v115
	v_lshlrev_b32_e32 v148, 16, v13
	v_and_b32_e32 v145, 0xffff0000, v123
	v_and_b32_e32 v147, 0xffff0000, v115
	v_and_b32_e32 v149, 0xffff0000, v13
	ds_read_b32 v0, v117
	ds_read_b128 v[10:13], v221
	ds_read_b128 v[112:115], v221 offset:16
	ds_read_b128 v[120:123], v221 offset:1536
	v_pk_mul_f32 v[124:125], v[118:119], v[124:125] op_sel_hi:[0,1]
	s_waitcnt lgkmcnt(0)
	v_pk_mul_f32 v[120:121], v[120:121], v[126:127]
	s_nop 0
	v_pk_fma_f32 v[10:11], v[124:125], v[10:11], v[120:121]
	ds_read_b128 v[124:127], v221 offset:3072
	v_pk_mul_f32 v[120:121], v[116:117], v[128:129] op_sel_hi:[0,1]
	ds_read_b128 v[128:131], v221 offset:4608
	s_waitcnt lgkmcnt(1)
	v_pk_fma_f32 v[10:11], v[120:121], v[124:125], v[10:11]
	s_waitcnt lgkmcnt(0)
	v_pk_add_f32 v[10:11], v[128:129], v[10:11]
	s_nop 0
	v_mul_f32_e32 v119, 0xbfb8aa3b, v10
	v_exp_f32_e32 v120, v119
	v_mul_f32_e32 v119, 0xbfb8aa3b, v11
	v_exp_f32_e32 v121, v119
	s_nop 0
	v_pk_add_f32 v[120:121], v[120:121], 1.0 op_sel_hi:[1,0]
	s_nop 0
	v_rcp_f32_e32 v124, v121
	s_nop 0
	v_mul_f32_e32 v11, v11, v124
	v_rcp_f32_e32 v121, v120
	s_nop 0
	v_mul_f32_e32 v10, v10, v121
	v_pk_mul_f32 v[128:129], v[10:11], s[2:3] op_sel_hi:[1,0]
	v_pk_mul_f32 v[10:11], v[118:119], v[132:133] op_sel_hi:[0,1]
	v_pk_mul_f32 v[120:121], v[122:123], v[134:135]
	s_nop 0
	v_pk_fma_f32 v[10:11], v[10:11], v[12:13], v[120:121]
	v_pk_mul_f32 v[12:13], v[116:117], v[136:137] op_sel_hi:[0,1]
	v_pk_fma_f32 v[10:11], v[12:13], v[126:127], v[10:11]
	ds_read_b128 v[124:127], v221 offset:4624
	v_pk_add_f32 v[10:11], v[130:131], v[10:11]
	s_nop 0
	v_mul_f32_e32 v12, 0xbfb8aa3b, v10
	v_mul_f32_e32 v13, 0xbfb8aa3b, v11
	v_exp_f32_e32 v12, v12
	v_exp_f32_e32 v13, v13
	s_nop 0
	v_pk_add_f32 v[12:13], v[12:13], 1.0 op_sel_hi:[1,0]
	s_nop 0
	v_rcp_f32_e32 v120, v13
	s_nop 0
	v_mul_f32_e32 v11, v11, v120
	v_rcp_f32_e32 v119, v12
	s_nop 0
	v_mul_f32_e32 v10, v10, v119
	v_pk_mul_f32 v[130:131], v[10:11], s[2:3] op_sel_hi:[1,0]
	ds_read_b128 v[10:13], v221 offset:1552
	v_pk_mul_f32 v[120:121], v[118:119], v[138:139] op_sel_hi:[0,1]
	s_waitcnt lgkmcnt(0)
	v_pk_mul_f32 v[10:11], v[10:11], v[140:141]
	s_nop 0
	v_pk_fma_f32 v[10:11], v[120:121], v[112:113], v[10:11]
	ds_read_b128 v[120:123], v221 offset:3088
	v_pk_mul_f32 v[112:113], v[116:117], v[142:143] op_sel_hi:[0,1]
	v_pk_mul_f32 v[12:13], v[12:13], v[146:147]
	s_waitcnt lgkmcnt(0)
	v_pk_fma_f32 v[10:11], v[112:113], v[120:121], v[10:11]
	s_nop 0
	v_pk_add_f32 v[10:11], v[124:125], v[10:11]
	s_nop 0
	v_mul_f32_e32 v112, 0xbfb8aa3b, v10
	v_mul_f32_e32 v113, 0xbfb8aa3b, v11
	v_exp_f32_e32 v112, v112
	v_exp_f32_e32 v113, v113
	s_nop 0
	v_pk_add_f32 v[112:113], v[112:113], 1.0 op_sel_hi:[1,0]
	s_nop 0
	v_rcp_f32_e32 v120, v113
	s_nop 0
	v_mul_f32_e32 v11, v11, v120
	v_rcp_f32_e32 v119, v112
	s_nop 0
	v_mul_f32_e32 v10, v10, v119
	v_pk_mul_f32 v[112:113], v[10:11], s[2:3] op_sel_hi:[1,0]
	v_pk_mul_f32 v[10:11], v[118:119], v[144:145] op_sel_hi:[0,1]
	v_pk_fma_f32 v[10:11], v[10:11], v[114:115], v[12:13]
	v_pk_mul_f32 v[12:13], v[116:117], v[148:149] op_sel_hi:[0,1]
	v_pk_fma_f32 v[10:11], v[12:13], v[122:123], v[10:11]
	s_nop 0
	v_pk_add_f32 v[10:11], v[126:127], v[10:11]
	s_nop 0
	v_mul_f32_e32 v12, 0xbfb8aa3b, v10
	v_mul_f32_e32 v13, 0xbfb8aa3b, v11
	v_exp_f32_e32 v12, v12
	v_exp_f32_e32 v13, v13
	s_nop 0
	v_pk_add_f32 v[12:13], v[12:13], 1.0 op_sel_hi:[1,0]
	s_nop 0
	v_rcp_f32_e32 v115, v13
	s_nop 0
	v_mul_f32_e32 v11, v11, v115
	v_rcp_f32_e32 v114, v12
	s_nop 0
	v_mul_f32_e32 v10, v10, v114
	v_pk_mul_f32 v[114:115], v[10:11], s[2:3] op_sel_hi:[1,0]
	v_cvt_pk_bf16_f32 v10, v128, v129
	v_cvt_pk_bf16_f32 v11, v130, v131
	v_cvt_pk_bf16_f32 v12, v112, v113
	v_cvt_pk_bf16_f32 v13, v114, v115
	ds_write_b128 v222, v[10:13] offset:25600
	v_mul_f32_e32 v10, v128, v0
	v_cvt_pk_bf16_f32 v10, v10, s0
	v_add_u32_e32 v11, v181, v223
	ds_write_b16 v11, v10 offset:51200
	v_mul_f32_e32 v10, v129, v0
	v_cvt_pk_bf16_f32 v10, v10, s0
	ds_write_b16 v11, v10 offset:51344
	v_mul_f32_e32 v10, v130, v0
	v_cvt_pk_bf16_f32 v10, v10, s0
	ds_write_b16 v11, v10 offset:51488
	v_mul_f32_e32 v10, v131, v0
	v_cvt_pk_bf16_f32 v10, v10, s0
	ds_write_b16 v11, v10 offset:51632
	v_mul_f32_e32 v10, v112, v0
	v_cvt_pk_bf16_f32 v10, v10, s0
	ds_write_b16 v11, v10 offset:51776
	v_mul_f32_e32 v10, v113, v0
	v_cvt_pk_bf16_f32 v10, v10, s0
	ds_write_b16 v11, v10 offset:51920
	v_mul_f32_e32 v10, v0, v114
	v_cvt_pk_bf16_f32 v10, v10, s0
	v_mul_f32_e32 v0, v0, v115
	ds_write_b16 v11, v10 offset:52064
	v_cvt_pk_bf16_f32 v0, v0, s0
	v_add_u32_e32 v10, v181, v224
	ds_write_b16 v10, v0 offset:51200
	s_waitcnt vmcnt(0)
	ds_read_b128 v[10:13], v208
	ds_read_b128 v[112:115], v217
	s_nop 0
	ds_read_b128 v[6:9], v218
	s_waitcnt lgkmcnt(0)
; DI unsigned pack2(float a, float b) { f32x2_t v = {a, b}; bf16x2_t r = __builtin_convertvector(v, bf16x2_t); return __builtin_bit_cast(unsigned, r); }
; DI void mlstm_job(const PX& p, int l, int job, unsigned char* smem) {
;     ...
;           } else {
;             const float wk = wkA[par * 64 + tau];
; #pragma unroll
;             for (int e = 0; e < 8; e++) v[e] *= 0.07216878364870323f;
;             uint4 o;
;             o.x = pack2(v[0], v[1]); o.y = pack2(v[2], v[3]); o.z = pack2(v[4], v[5]); o.w = pack2(v[6], v[7]);
;             *(uint4*)(sk + tau * 200 + d8) = o;
; #pragma unroll
;             for (int e = 0; e < 8; e++) swk[(d8 + e) * 72 + tau] = f2bf(wk * v[e]);
;           }
;         } else {
;           const bfu* zp = Zml + (size_t)tok * 3072 + 1536 + h * 192 + d8;
;           const uint4 mid = *(const uint4*)zp;
;           const unsigned mm_[4] = {mid.x, mid.y, mid.z, mid.w};
; #pragma unroll
;           for (int e = 0; e < 8; e++) svT[(d8 + e) * 72 + tau] = (bfu)((e & 1) ? (mm_[e >> 1] >> 16) : (mm_[e >> 1] & 0xffffu));
;         }
	s_add_i32 m0, s82, 0x20500
	s_nop 0
	global_load_lds_dwordx4 v[14:15], off offset:3072
	s_add_i32 m0, s82, 0x22480
	s_nop 0
	global_load_lds_dwordx4 v[14:15], off offset:3200
	s_add_i32 m0, s82, 0x24400
	s_nop 0
	global_load_lds_dwordx4 v[14:15], off offset:3328
	s_nop 0
	v_lshlrev_b32_e32 v122, 16, v10
	s_nop 0
	v_lshlrev_b32_e32 v120, 16, v112
	s_nop 0
	v_lshlrev_b32_e32 v124, 16, v6
	v_and_b32_e32 v121, 0xffff0000, v112
	v_and_b32_e32 v123, 0xffff0000, v10
	v_and_b32_e32 v125, 0xffff0000, v6
	v_lshlrev_b32_e32 v128, 16, v113
	v_lshlrev_b32_e32 v130, 16, v11
	v_lshlrev_b32_e32 v132, 16, v7
	v_and_b32_e32 v129, 0xffff0000, v113
	v_and_b32_e32 v131, 0xffff0000, v11
	v_and_b32_e32 v133, 0xffff0000, v7
	v_lshlrev_b32_e32 v134, 16, v114
	v_lshlrev_b32_e32 v136, 16, v12
	v_lshlrev_b32_e32 v138, 16, v8
	v_and_b32_e32 v135, 0xffff0000, v114
	v_and_b32_e32 v137, 0xffff0000, v12
	v_and_b32_e32 v139, 0xffff0000, v8
	v_lshlrev_b32_e32 v140, 16, v115
	v_lshlrev_b32_e32 v142, 16, v13
	v_lshlrev_b32_e32 v144, 16, v9
	v_and_b32_e32 v141, 0xffff0000, v115
	v_and_b32_e32 v143, 0xffff0000, v13
	v_and_b32_e32 v145, 0xffff0000, v9
	ds_read_b32 v0, v117
	ds_read_b128 v[6:9], v225
	ds_read_b128 v[10:13], v225 offset:16
	ds_read_b128 v[112:115], v225 offset:1536
	v_pk_mul_f32 v[120:121], v[118:119], v[120:121] op_sel_hi:[0,1]
	s_waitcnt lgkmcnt(0)
	v_pk_mul_f32 v[112:113], v[112:113], v[122:123]
	s_nop 0
	v_pk_fma_f32 v[6:7], v[120:121], v[6:7], v[112:113]
	ds_read_b128 v[120:123], v225 offset:3072
	v_pk_mul_f32 v[112:113], v[116:117], v[124:125] op_sel_hi:[0,1]
	ds_read_b128 v[124:127], v225 offset:4608
	s_waitcnt lgkmcnt(1)
	v_pk_fma_f32 v[6:7], v[112:113], v[120:121], v[6:7]
	s_waitcnt lgkmcnt(0)
	v_pk_add_f32 v[6:7], v[124:125], v[6:7]
	s_nop 0
	v_mul_f32_e32 v112, 0xbfb8aa3b, v6
	v_mul_f32_e32 v113, 0xbfb8aa3b, v7
	v_exp_f32_e32 v112, v112
	v_exp_f32_e32 v113, v113
	s_nop 0
	v_pk_add_f32 v[112:113], v[112:113], 1.0 op_sel_hi:[1,0]
	s_nop 0
	v_rcp_f32_e32 v119, v113
	s_nop 0
	v_mul_f32_e32 v7, v7, v119
	v_rcp_f32_e32 v117, v112
	s_nop 0
	v_mul_f32_e32 v6, v6, v117
	v_pk_mul_f32 v[124:125], v[6:7], s[2:3] op_sel_hi:[1,0]
	v_pk_mul_f32 v[6:7], v[118:119], v[128:129] op_sel_hi:[0,1]
	v_pk_mul_f32 v[112:113], v[114:115], v[130:131]
	s_nop 0
	v_pk_fma_f32 v[6:7], v[6:7], v[8:9], v[112:113]
	v_pk_mul_f32 v[8:9], v[116:117], v[132:133] op_sel_hi:[0,1]
	v_pk_fma_f32 v[6:7], v[8:9], v[122:123], v[6:7]
	ds_read_b128 v[120:123], v225 offset:4624
	v_pk_add_f32 v[6:7], v[126:127], v[6:7]
	s_nop 0
	v_mul_f32_e32 v8, 0xbfb8aa3b, v6
	v_mul_f32_e32 v9, 0xbfb8aa3b, v7
	v_exp_f32_e32 v8, v8
	v_exp_f32_e32 v9, v9
	s_nop 0
	v_pk_add_f32 v[8:9], v[8:9], 1.0 op_sel_hi:[1,0]
	s_nop 0
	v_rcp_f32_e32 v113, v9
	s_nop 0
	v_mul_f32_e32 v7, v7, v113
	v_rcp_f32_e32 v112, v8
	s_nop 0
	v_mul_f32_e32 v6, v6, v112
	v_pk_mul_f32 v[126:127], v[6:7], s[2:3] op_sel_hi:[1,0]
	ds_read_b128 v[6:9], v225 offset:1552
	v_pk_mul_f32 v[112:113], v[118:119], v[134:135] op_sel_hi:[0,1]
	s_waitcnt lgkmcnt(0)
	v_pk_mul_f32 v[6:7], v[6:7], v[136:137]
	s_nop 0
	v_pk_fma_f32 v[6:7], v[112:113], v[10:11], v[6:7]
	ds_read_b128 v[112:115], v225 offset:3088
	v_pk_mul_f32 v[10:11], v[116:117], v[138:139] op_sel_hi:[0,1]
	v_pk_mul_f32 v[8:9], v[8:9], v[142:143]
	s_waitcnt lgkmcnt(0)
	v_pk_fma_f32 v[6:7], v[10:11], v[112:113], v[6:7]
	s_nop 0
	v_pk_add_f32 v[6:7], v[120:121], v[6:7]
	s_nop 0
	v_mul_f32_e32 v10, 0xbfb8aa3b, v6
	v_mul_f32_e32 v11, 0xbfb8aa3b, v7
	v_exp_f32_e32 v10, v10
	v_exp_f32_e32 v11, v11
	s_nop 0
	v_pk_add_f32 v[10:11], v[10:11], 1.0 op_sel_hi:[1,0]
	s_nop 0
	v_rcp_f32_e32 v113, v11
	s_nop 0
	v_mul_f32_e32 v7, v7, v113
	v_rcp_f32_e32 v112, v10
	s_nop 0
	v_mul_f32_e32 v6, v6, v112
	v_pk_mul_f32 v[10:11], v[6:7], s[2:3] op_sel_hi:[1,0]
	v_pk_mul_f32 v[6:7], v[118:119], v[140:141] op_sel_hi:[0,1]
	v_pk_fma_f32 v[6:7], v[6:7], v[12:13], v[8:9]
	v_pk_mul_f32 v[8:9], v[116:117], v[144:145] op_sel_hi:[0,1]
	v_pk_fma_f32 v[6:7], v[8:9], v[114:115], v[6:7]
	s_nop 0
	v_pk_add_f32 v[6:7], v[122:123], v[6:7]
	s_nop 0
	v_mul_f32_e32 v8, 0xbfb8aa3b, v6
	v_mul_f32_e32 v9, 0xbfb8aa3b, v7
	v_exp_f32_e32 v8, v8
	v_exp_f32_e32 v9, v9
	s_nop 0
	v_pk_add_f32 v[8:9], v[8:9], 1.0 op_sel_hi:[1,0]
	s_nop 0
	v_rcp_f32_e32 v13, v9
	s_nop 0
	v_mul_f32_e32 v7, v7, v13
	v_rcp_f32_e32 v12, v8
	s_nop 0
	v_mul_f32_e32 v6, v6, v12
	v_pk_mul_f32 v[12:13], v[6:7], s[2:3] op_sel_hi:[1,0]
	v_cvt_pk_bf16_f32 v6, v124, v125
	v_cvt_pk_bf16_f32 v7, v126, v127
	v_cvt_pk_bf16_f32 v8, v10, v11
	v_cvt_pk_bf16_f32 v9, v12, v13
	ds_write_b128 v226, v[6:9] offset:25600
	v_mul_f32_e32 v6, v124, v0
	v_cvt_pk_bf16_f32 v6, v6, s0
	v_add_u32_e32 v7, v181, v227
	ds_write_b16 v7, v6 offset:51200
	v_mul_f32_e32 v6, v125, v0
	v_cvt_pk_bf16_f32 v6, v6, s0
	ds_write_b16 v7, v6 offset:51344
	v_mul_f32_e32 v6, v126, v0
	v_cvt_pk_bf16_f32 v6, v6, s0
	ds_write_b16 v7, v6 offset:51488
	v_mul_f32_e32 v6, v127, v0
	v_cvt_pk_bf16_f32 v6, v6, s0
	ds_write_b16 v7, v6 offset:51632
	v_mul_f32_e32 v6, v10, v0
	v_cvt_pk_bf16_f32 v6, v6, s0
	ds_write_b16 v7, v6 offset:51776
	v_mul_f32_e32 v6, v11, v0
	v_cvt_pk_bf16_f32 v6, v6, s0
	ds_write_b16 v7, v6 offset:51920
	v_mul_f32_e32 v6, v0, v12
	v_cvt_pk_bf16_f32 v6, v6, s0
	v_mul_f32_e32 v0, v0, v13
	ds_write_b16 v7, v6 offset:52064
	v_cvt_pk_bf16_f32 v0, v0, s0
	v_add_u32_e32 v6, v181, v228
	ds_write_b16 v6, v0 offset:51200
	s_waitcnt vmcnt(0)
	ds_read_b128 v[6:9], v208
	v_add_u32_e32 v0, v179, v219
	s_waitcnt lgkmcnt(0)
	ds_write_b16 v0, v6
	ds_write_b16_d16_hi v0, v6 offset:144
	ds_write_b16 v0, v7 offset:288
	ds_write_b16_d16_hi v0, v7 offset:432
	ds_write_b16 v0, v8 offset:576
	ds_write_b16_d16_hi v0, v8 offset:720
	ds_write_b16 v0, v9 offset:864
	ds_read_b128 v[4:7], v208 offset:8192
	v_add_u32_e32 v0, v179, v220
	ds_write_b16_d16_hi v0, v9
	v_add_u32_e32 v0, v179, v223
	s_waitcnt lgkmcnt(0)
; DI void mlstm_job(const PX& p, int l, int job, unsigned char* smem) {
;     ...
;         } else {
;           const bfu* zp = Zml + (size_t)tok * 3072 + 1536 + h * 192 + d8;
;           const uint4 mid = *(const uint4*)zp;
;           const unsigned mm_[4] = {mid.x, mid.y, mid.z, mid.w};
; #pragma unroll
;           for (int e = 0; e < 8; e++) svT[(d8 + e) * 72 + tau] = (bfu)((e & 1) ? (mm_[e >> 1] >> 16) : (mm_[e >> 1] & 0xffffu));
;         }
;       }
;       __syncthreads();
;       f32x16 num[2];
; #pragma unroll
;       for (int r = 0; r < 16; r++) { num[0][r] = 0.f; num[1][r] = 0.f; }
;       if (w < 7) {
	ds_write_b16 v0, v4
	ds_write_b16_d16_hi v0, v4 offset:144
	ds_write_b16 v0, v5 offset:288
	ds_write_b16_d16_hi v0, v5 offset:432
	ds_write_b16 v0, v6 offset:576
	ds_write_b16_d16_hi v0, v6 offset:720
	ds_write_b16 v0, v7 offset:864
	ds_read_b128 v[2:5], v208 offset:16384
	v_add_u32_e32 v0, v179, v224
	ds_write_b16_d16_hi v0, v7
	v_add_u32_e32 v0, v179, v227
	s_waitcnt lgkmcnt(0)
	ds_write_b16 v0, v2
	ds_write_b16_d16_hi v0, v2 offset:144
	ds_write_b16 v0, v3 offset:288
	ds_write_b16_d16_hi v0, v3 offset:432
	ds_write_b16 v0, v4 offset:576
	ds_write_b16_d16_hi v0, v4 offset:720
	ds_write_b16 v0, v5 offset:864
	v_add_u32_e32 v0, v179, v228
	v_mov_b32_e32 v14, v1
	v_mov_b32_e32 v15, v1
	ds_write_b16_d16_hi v0, v5
	v_mov_b32_e32 v0, v1
	v_mov_b32_e32 v2, v1
	v_mov_b32_e32 v3, v1
	v_mov_b32_e32 v4, v1
	v_mov_b32_e32 v5, v1
	v_mov_b32_e32 v6, v1
	v_mov_b32_e32 v7, v1
	v_mov_b32_e32 v8, v1
	v_mov_b32_e32 v9, v1
	v_mov_b32_e32 v10, v1
	v_mov_b32_e32 v11, v1
	v_mov_b32_e32 v12, v1
	v_mov_b32_e32 v13, v1
	v_mov_b64_e32 v[126:127], v[14:15]
	v_mov_b64_e32 v[142:143], v[14:15]
	v_mov_b64_e32 v[124:125], v[12:13]
	v_mov_b64_e32 v[122:123], v[10:11]
	v_mov_b64_e32 v[120:121], v[8:9]
	v_mov_b64_e32 v[118:119], v[6:7]
	v_mov_b64_e32 v[116:117], v[4:5]
	v_mov_b64_e32 v[114:115], v[2:3]
	v_mov_b64_e32 v[112:113], v[0:1]
	v_mov_b64_e32 v[140:141], v[12:13]
	v_mov_b64_e32 v[138:139], v[10:11]
	v_mov_b64_e32 v[136:137], v[8:9]
	v_mov_b64_e32 v[134:135], v[6:7]
	v_mov_b64_e32 v[132:133], v[4:5]
	v_mov_b64_e32 v[130:131], v[2:3]
	v_mov_b64_e32 v[128:129], v[0:1]
	s_waitcnt lgkmcnt(0)
	s_barrier
	s_and_saveexec_b64 s[62:63], s[8:9]
	s_cbranch_execz .LBB0_456
; DI unsigned pack2(float a, float b) { f32x2_t v = {a, b}; bf16x2_t r = __builtin_convertvector(v, bf16x2_t); return __builtin_bit_cast(unsigned, r); }
; DI f32x16 mfma32(bf16x8 a, bf16x8 b, f32x16 c) { return __builtin_amdgcn_mfma_f32_32x32x16_bf16(a, b, c, 0, 0, 0); }
; DI void mlstm_job(const PX& p, int l, int job, unsigned char* smem) {
;     ...
;       if (w < 7) {
; #pragma unroll
;         for (int i = 0; i < 6; i++) {
; #pragma unroll
;           for (int s2 = 0; s2 < 2; s2++) {
;             uint4 pk;
;             pk.x = pack2(st[i][8 * s2 + 0], st[i][8 * s2 + 1]);
;             pk.y = pack2(st[i][8 * s2 + 2], st[i][8 * s2 + 3]);
;             pk.z = pack2(st[i][8 * s2 + 4], st[i][8 * s2 + 5]);
;             pk.w = pack2(st[i][8 * s2 + 6], st[i][8 * s2 + 7]);
;             const bf16x8 aop = u4_to_bf8(pk);
; #pragma unroll
;             for (int ti = 0; ti < 2; ti++) {
;               const bfu* qp = sq + (ti * 32 + lr) * 200 + 32 * i + 16 * s2 + 4 * lh;
;               const uint2 lo = *(const uint2*)qp;
;               const uint2 hi = *(const uint2*)(qp + 8);
;               const uint4 bq = make_uint4(lo.x, lo.y, hi.x, hi.y);
;               num[ti] = mfma32(aop, u4_to_bf8(bq), num[ti]);
;             }
;           }
;         }
; #pragma unroll
;         for (int ti = 0; ti < 2; ti++) {
;           const float wi = winA[par * 64 + ti * 32 + lr];
; #pragma unroll
;           for (int r = 0; r < 16; r++) num[ti][r] *= wi;
;         }
;       }
	v_add_u32_e32 v0, 0x3000, v215
	ds_read2_b64 v[6:9], v215 offset1:2
	ds_read2_b64 v[10:13], v0 offset0:64 offset1:66
	ds_read2_b64 v[144:147], v215 offset0:4 offset1:6
	ds_read2_b64 v[148:151], v0 offset0:68 offset1:70
	v_cvt_pk_bf16_f32 v2, v96, v97
	v_cvt_pk_bf16_f32 v3, v98, v99
	v_cvt_pk_bf16_f32 v4, v100, v101
	v_cvt_pk_bf16_f32 v5, v102, v103
	s_waitcnt lgkmcnt(3)
	s_nop 0
	v_mfma_f32_32x32x16_bf16 v[128:143], v[2:5], v[6:9], 0
	ds_read2_b64 v[6:9], v215 offset0:8 offset1:10
	s_waitcnt lgkmcnt(3)
	v_mfma_f32_32x32x16_bf16 v[112:127], v[2:5], v[10:13], 0
	ds_read2_b64 v[10:13], v0 offset0:72 offset1:74
	v_cvt_pk_bf16_f32 v2, v104, v105
	v_cvt_pk_bf16_f32 v3, v106, v107
	v_cvt_pk_bf16_f32 v4, v108, v109
	v_cvt_pk_bf16_f32 v5, v110, v111
	s_waitcnt lgkmcnt(3)
	s_nop 0
	v_mfma_f32_32x32x16_bf16 v[128:143], v[2:5], v[144:147], v[128:143]
	ds_read2_b64 v[144:147], v215 offset0:12 offset1:14
	s_waitcnt lgkmcnt(3)
	v_mfma_f32_32x32x16_bf16 v[112:127], v[2:5], v[148:151], v[112:127]
	ds_read2_b64 v[148:151], v0 offset0:76 offset1:78
	v_cvt_pk_bf16_f32 v2, v80, v81
	v_cvt_pk_bf16_f32 v3, v82, v83
	v_cvt_pk_bf16_f32 v4, v84, v85
	v_cvt_pk_bf16_f32 v5, v86, v87
	s_waitcnt lgkmcnt(3)
	s_nop 0
	v_mfma_f32_32x32x16_bf16 v[128:143], v[2:5], v[6:9], v[128:143]
	ds_read2_b64 v[6:9], v215 offset0:16 offset1:18
	s_waitcnt lgkmcnt(3)
	v_mfma_f32_32x32x16_bf16 v[112:127], v[2:5], v[10:13], v[112:127]
	ds_read2_b64 v[10:13], v0 offset0:80 offset1:82
	v_cvt_pk_bf16_f32 v2, v88, v89
	v_cvt_pk_bf16_f32 v3, v90, v91
	v_cvt_pk_bf16_f32 v4, v92, v93
	v_cvt_pk_bf16_f32 v5, v94, v95
	s_waitcnt lgkmcnt(3)
	s_nop 0
	v_mfma_f32_32x32x16_bf16 v[128:143], v[2:5], v[144:147], v[128:143]
	ds_read2_b64 v[144:147], v215 offset0:20 offset1:22
	s_waitcnt lgkmcnt(3)
	v_mfma_f32_32x32x16_bf16 v[112:127], v[2:5], v[148:151], v[112:127]
	ds_read2_b64 v[148:151], v0 offset0:84 offset1:86
	v_cvt_pk_bf16_f32 v2, v64, v65
	v_cvt_pk_bf16_f32 v3, v66, v67
	v_cvt_pk_bf16_f32 v4, v68, v69
	v_cvt_pk_bf16_f32 v5, v70, v71
	s_waitcnt lgkmcnt(3)
	s_nop 0
	v_mfma_f32_32x32x16_bf16 v[128:143], v[2:5], v[6:9], v[128:143]
	ds_read2_b64 v[6:9], v215 offset0:24 offset1:26
	s_waitcnt lgkmcnt(3)
	v_mfma_f32_32x32x16_bf16 v[112:127], v[2:5], v[10:13], v[112:127]
	ds_read2_b64 v[10:13], v0 offset0:88 offset1:90
	v_cvt_pk_bf16_f32 v2, v72, v73
	v_cvt_pk_bf16_f32 v3, v74, v75
	v_cvt_pk_bf16_f32 v4, v76, v77
	v_cvt_pk_bf16_f32 v5, v78, v79
	s_waitcnt lgkmcnt(3)
	s_nop 0
	v_mfma_f32_32x32x16_bf16 v[128:143], v[2:5], v[144:147], v[128:143]
	ds_read2_b64 v[144:147], v215 offset0:28 offset1:30
	s_waitcnt lgkmcnt(3)
	v_mfma_f32_32x32x16_bf16 v[112:127], v[2:5], v[148:151], v[112:127]
	ds_read2_b64 v[148:151], v0 offset0:92 offset1:94
	v_cvt_pk_bf16_f32 v2, v48, v49
	v_cvt_pk_bf16_f32 v3, v50, v51
	v_cvt_pk_bf16_f32 v4, v52, v53
	v_cvt_pk_bf16_f32 v5, v54, v55
	s_waitcnt lgkmcnt(3)
	s_nop 0
	v_mfma_f32_32x32x16_bf16 v[128:143], v[2:5], v[6:9], v[128:143]
	ds_read2_b64 v[6:9], v215 offset0:32 offset1:34
	s_waitcnt lgkmcnt(3)
	v_mfma_f32_32x32x16_bf16 v[112:127], v[2:5], v[10:13], v[112:127]
	ds_read2_b64 v[10:13], v0 offset0:96 offset1:98
	v_cvt_pk_bf16_f32 v2, v56, v57
	v_cvt_pk_bf16_f32 v3, v58, v59
	v_cvt_pk_bf16_f32 v4, v60, v61
	v_cvt_pk_bf16_f32 v5, v62, v63
	s_waitcnt lgkmcnt(3)
	s_nop 0
	v_mfma_f32_32x32x16_bf16 v[128:143], v[2:5], v[144:147], v[128:143]
	ds_read2_b64 v[144:147], v215 offset0:36 offset1:38
	s_waitcnt lgkmcnt(3)
	v_mfma_f32_32x32x16_bf16 v[112:127], v[2:5], v[148:151], v[112:127]
	ds_read2_b64 v[148:151], v0 offset0:100 offset1:102
	v_cvt_pk_bf16_f32 v2, v32, v33
	v_cvt_pk_bf16_f32 v3, v34, v35
	v_cvt_pk_bf16_f32 v4, v36, v37
	v_cvt_pk_bf16_f32 v5, v38, v39
	s_waitcnt lgkmcnt(3)
	s_nop 0
	v_mfma_f32_32x32x16_bf16 v[128:143], v[2:5], v[6:9], v[128:143]
	ds_read2_b64 v[6:9], v215 offset0:40 offset1:42
	s_waitcnt lgkmcnt(3)
	v_mfma_f32_32x32x16_bf16 v[112:127], v[2:5], v[10:13], v[112:127]
	ds_read2_b64 v[10:13], v0 offset0:104 offset1:106
	v_cvt_pk_bf16_f32 v2, v40, v41
	v_cvt_pk_bf16_f32 v3, v42, v43
	v_cvt_pk_bf16_f32 v4, v44, v45
	v_cvt_pk_bf16_f32 v5, v46, v47
	s_waitcnt lgkmcnt(3)
	s_nop 0
	v_mfma_f32_32x32x16_bf16 v[128:143], v[2:5], v[144:147], v[128:143]
	ds_read2_b64 v[144:147], v215 offset0:44 offset1:46
	s_waitcnt lgkmcnt(3)
	v_mfma_f32_32x32x16_bf16 v[112:127], v[2:5], v[148:151], v[112:127]
	ds_read2_b64 v[148:151], v0 offset0:108 offset1:110
	v_cvt_pk_bf16_f32 v2, v16, v17
	v_cvt_pk_bf16_f32 v3, v18, v19
	v_cvt_pk_bf16_f32 v4, v20, v21
	v_cvt_pk_bf16_f32 v5, v22, v23
	s_waitcnt lgkmcnt(3)
	s_nop 0
	v_mfma_f32_32x32x16_bf16 v[128:143], v[2:5], v[6:9], v[128:143]
	s_waitcnt lgkmcnt(2)
	v_mfma_f32_32x32x16_bf16 v[112:127], v[2:5], v[10:13], v[112:127]
	v_cvt_pk_bf16_f32 v2, v24, v25
	v_cvt_pk_bf16_f32 v3, v26, v27
	v_cvt_pk_bf16_f32 v4, v28, v29
	v_cvt_pk_bf16_f32 v5, v30, v31
	s_waitcnt lgkmcnt(1)
	s_nop 0
	v_mfma_f32_32x32x16_bf16 v[128:143], v[2:5], v[144:147], v[128:143]
	s_waitcnt lgkmcnt(0)
	v_mfma_f32_32x32x16_bf16 v[112:127], v[2:5], v[148:151], v[112:127]
	v_add_u32_e32 v0, s27, v182
	ds_read2_b32 v[2:3], v0 offset1:32
	s_waitcnt lgkmcnt(0)
	v_mov_b32_e32 v0, v3
	s_nop 6
	v_mul_f32_e64 v142, v142, v2
	v_mul_f32_e64 v143, v143, v2
	v_pk_mul_f32 v[140:141], v[140:141], v[2:3] op_sel_hi:[1,0]
	v_pk_mul_f32 v[138:139], v[138:139], v[2:3] op_sel_hi:[1,0]
	v_pk_mul_f32 v[136:137], v[136:137], v[2:3] op_sel_hi:[1,0]
	v_pk_mul_f32 v[134:135], v[134:135], v[2:3] op_sel_hi:[1,0]
	v_pk_mul_f32 v[132:133], v[132:133], v[2:3] op_sel_hi:[1,0]
	v_pk_mul_f32 v[130:131], v[130:131], v[2:3] op_sel_hi:[1,0]
	v_pk_mul_f32 v[128:129], v[128:129], v[2:3] op_sel_hi:[1,0]
	v_pk_mul_f32 v[126:127], v[126:127], v[0:1] op_sel_hi:[1,0]
	v_pk_mul_f32 v[124:125], v[124:125], v[0:1] op_sel_hi:[1,0]
	v_pk_mul_f32 v[122:123], v[122:123], v[0:1] op_sel_hi:[1,0]
	v_pk_mul_f32 v[120:121], v[120:121], v[0:1] op_sel_hi:[1,0]
	v_pk_mul_f32 v[118:119], v[118:119], v[0:1] op_sel_hi:[1,0]
	v_pk_mul_f32 v[116:117], v[116:117], v[0:1] op_sel_hi:[1,0]
	v_pk_mul_f32 v[114:115], v[114:115], v[0:1] op_sel_hi:[1,0]
	v_pk_mul_f32 v[112:113], v[112:113], v[0:1] op_sel_hi:[1,0]
